# phase 0 weight transposes: non-temporal loads for the once-read f32 weights
# baseline (speedup 1.0000x reference)
.LBB0_37:
	s_lshl_b64 s[18:19], s[2:3], 2
	s_add_u32 s14, s14, s18
	s_addc_u32 s15, s15, s19
	v_or_b32_e32 v4, s26, v1
	v_lshl_add_u64 v[2:3], s[14:15], 0, v[28:29]
	v_mul_hi_u32_u24_e32 v5, s16, v4
	v_mul_u32_u24_e32 v4, s16, v4
	v_lshl_add_u64 v[10:11], v[4:5], 2, v[2:3]
	v_add_u32_e32 v4, s26, v30
	v_mul_hi_u32_u24_e32 v5, s16, v4
	v_mul_u32_u24_e32 v4, s16, v4
	v_lshl_add_u64 v[12:13], v[4:5], 2, v[2:3]
	global_load_dwordx4 v[6:9], v[10:11], off nt
	global_load_dwordx4 v[2:5], v[12:13], off nt
	s_cmpk_gt_i32 s34, 0x3fe
	s_cselect_b64 s[18:19], -1, 0
	s_cmpk_lt_i32 s34, 0x3ff
	s_mov_b64 s[26:27], -1
	s_cbranch_scc1 .LBB0_51
	s_cmpk_lt_u32 s34, 0x600
	s_cbranch_scc1 .LBB0_48
	s_cmpk_lt_u32 s34, 0x800
	s_cbranch_scc1 .LBB0_45
	s_cmpk_lt_u32 s34, 0x1800
	s_mov_b64 s[16:17], -1
	s_cbranch_scc1 .LBB0_42
	s_add_i32 s2, s34, 0xffffe801
	s_lshr_b32 s2, s2, 10
	s_add_i32 s14, s48, 64
	s_and_b32 s28, s44, 0xfc0
	s_and_b32 s26, s14, 0x340
	s_lshl_b64 s[14:15], s[2:3], 24
	s_add_u32 s14, s10, s14
	s_addc_u32 s15, s11, s15
	s_mov_b64 s[16:17], 0
	s_mov_b32 s2, s26

.LBB0_53:
	s_lshl_b64 s[26:27], s[2:3], 2
	s_add_u32 s14, s14, s26
	s_addc_u32 s15, s15, s27
	v_or_b32_e32 v12, s28, v1
	v_lshl_add_u64 v[10:11], s[14:15], 0, v[28:29]
	v_mul_hi_u32_u24_e32 v13, s16, v12
	v_mul_u32_u24_e32 v12, s16, v12
	v_lshl_add_u64 v[18:19], v[12:13], 2, v[10:11]
	v_add_u32_e32 v12, s28, v30
	v_mul_hi_u32_u24_e32 v13, s16, v12
	v_mul_u32_u24_e32 v12, s16, v12
	v_lshl_add_u64 v[20:21], v[12:13], 2, v[10:11]
	global_load_dwordx4 v[14:17], v[18:19], off nt
	global_load_dwordx4 v[10:13], v[20:21], off nt
	s_cmpk_gt_i32 s34, 0x3fd
	s_cselect_b64 s[16:17], -1, 0
	s_cmpk_lt_i32 s34, 0x3fe
	s_mov_b64 s[28:29], -1
	s_cbranch_scc1 .LBB0_67
	s_cmpk_lt_u32 s34, 0x600
	s_cbranch_scc1 .LBB0_64
	s_cmpk_lt_u32 s34, 0x800
	s_cbranch_scc1 .LBB0_61
	s_cmpk_lt_u32 s34, 0x1800
	s_mov_b64 s[26:27], -1
	s_cbranch_scc1 .LBB0_58
	s_add_i32 s2, s34, 0xffffe802
	s_lshr_b32 s2, s2, 10
	s_add_i32 s14, s48, 0x80
	s_and_b32 s30, s44, 0xfc0
	s_and_b32 s28, s14, 0x380
	s_lshl_b64 s[14:15], s[2:3], 24
	s_add_u32 s14, s10, s14
	s_addc_u32 s15, s11, s15
	s_mov_b64 s[26:27], 0
	s_mov_b32 s2, s28

.LBB0_69:
	s_lshl_b64 s[28:29], s[2:3], 2
	s_add_u32 s14, s14, s28
	s_addc_u32 s15, s15, s29
	v_or_b32_e32 v20, s30, v1
	v_lshl_add_u64 v[18:19], s[14:15], 0, v[28:29]
	v_mul_hi_u32_u24_e32 v21, s26, v20
	v_mul_u32_u24_e32 v20, s26, v20
	v_lshl_add_u64 v[42:43], v[20:21], 2, v[18:19]
	v_add_u32_e32 v20, s30, v30
	v_mul_hi_u32_u24_e32 v21, s26, v20
	v_mul_u32_u24_e32 v20, s26, v20
	v_lshl_add_u64 v[44:45], v[20:21], 2, v[18:19]
	global_load_dwordx4 v[22:25], v[42:43], off nt
	global_load_dwordx4 v[18:21], v[44:45], off nt
	s_cmpk_gt_i32 s34, 0x3fc
	s_cselect_b64 s[14:15], -1, 0
	s_cmpk_lt_i32 s34, 0x3fd
	s_mov_b64 s[30:31], -1
	s_cbranch_scc1 .LBB0_83
	s_cmpk_lt_u32 s34, 0x600
	s_cbranch_scc1 .LBB0_80
	s_cmpk_lt_u32 s34, 0x800
	s_cbranch_scc1 .LBB0_77
	s_cmpk_lt_u32 s34, 0x1800
	s_mov_b64 s[28:29], -1
	s_cbranch_scc1 .LBB0_74
	s_add_i32 s2, s34, 0xffffe803
	s_lshr_b32 s2, s2, 10
	s_add_i32 s26, s48, 0xc0
	s_and_b32 s50, s44, 0xfc0
	s_and_b32 s30, s26, 0x3c0
	s_lshl_b64 s[26:27], s[2:3], 24
	s_add_u32 s26, s10, s26
	s_addc_u32 s27, s11, s27
	s_mov_b64 s[28:29], 0
	s_mov_b32 s2, s30

.LBB0_85:
	s_lshl_b64 s[30:31], s[2:3], 2
	s_add_u32 s26, s26, s30
	s_addc_u32 s27, s27, s31
	v_or_b32_e32 v42, s50, v1
	v_lshl_add_u64 v[46:47], s[26:27], 0, v[28:29]
	v_mul_hi_u32_u24_e32 v43, s28, v42
	v_mul_u32_u24_e32 v42, s28, v42
	v_lshl_add_u64 v[42:43], v[42:43], 2, v[46:47]
	v_add_u32_e32 v48, s50, v30
	global_load_dwordx4 v[42:45], v[42:43], off nt
	v_mul_hi_u32_u24_e32 v49, s28, v48
	v_mul_u32_u24_e32 v48, s28, v48
	v_lshl_add_u64 v[46:47], v[48:49], 2, v[46:47]
	global_load_dwordx4 v[46:49], v[46:47], off nt
	s_waitcnt vmcnt(7)
	ds_write2_b32 v33, v6, v7 offset1:1
	ds_write2_b32 v33, v8, v9 offset0:2 offset1:3
	s_waitcnt vmcnt(6)
	ds_write2_b32 v34, v2, v3 offset1:1
	ds_write2_b32 v34, v4, v5 offset0:2 offset1:3
	s_waitcnt vmcnt(5)
	ds_write2_b32 v35, v14, v15 offset1:1
	ds_write2_b32 v36, v16, v17 offset1:1
	s_waitcnt vmcnt(4)
	ds_write2_b32 v37, v10, v11 offset1:1
	ds_write2_b32 v38, v12, v13 offset1:1
	s_waitcnt vmcnt(3)
	ds_write2_b32 v39, v22, v23 offset1:1
	ds_write2_b32 v40, v24, v25 offset1:1
	v_add_u32_e32 v2, 0x8200, v34
	v_add_u32_e32 v4, 0xc300, v33
	s_mov_b64 s[30:31], -1
	s_and_b64 vcc, exec, s[24:25]
	v_add_u32_e32 v3, 0x8208, v34
	v_add_u32_e32 v5, 0xc308, v33
	v_add_u32_e32 v6, 0xc300, v34
	v_add_u32_e32 v7, 0xc308, v34
	s_waitcnt vmcnt(2)
	ds_write2_b32 v2, v18, v19 offset1:1
	ds_write2_b32 v3, v20, v21 offset1:1
	s_waitcnt vmcnt(1)
	ds_write2_b32 v4, v42, v43 offset1:1
	ds_write2_b32 v5, v44, v45 offset1:1
	s_waitcnt vmcnt(0)
	ds_write2_b32 v6, v46, v47 offset1:1
	ds_write2_b32 v7, v48, v49 offset1:1
	s_waitcnt lgkmcnt(0)
	s_barrier
	s_cbranch_vccz .LBB0_99
	s_cmpk_gt_u32 s34, 0x5ff
	s_mov_b64 s[24:25], -1
	s_cbranch_scc0 .LBB0_96
	s_cmpk_gt_u32 s34, 0x7ff
	s_cbranch_scc0 .LBB0_93
	s_cmpk_gt_u32 s34, 0x17ff
	s_cbranch_scc0 .LBB0_90
	s_add_i32 s2, s34, 0xffffe800
	s_lshr_b32 s2, s2, 10
	s_and_b32 s28, s44, 0xfc0
	s_and_b32 s50, s48, 0x300
	s_lshl_b64 s[24:25], s[2:3], 23
	s_add_u32 s26, s35, s24
	s_addc_u32 s27, s36, s25
	s_mov_b64 s[24:25], 0
	s_mov_b32 s2, s28
